# software prefetch strategy: phase D prologue touches the tile's g0/g1 gate slabs (one discarded dword load per 128-B line) so the first merge epilogue reads them from L2/MALL instead of HBM
# baseline (speedup 1.0000x reference)
; __device__ __forceinline__ int lane_fresh() { int l; asm volatile("v_mbcnt_lo_u32_b32 %0, -1, 0\n\tv_mbcnt_hi_u32_b32 %0, -1, %0" : "=v"(l)); return l; }
; #define ACC_ZERO(acc) do { _Pragma("unroll") for (int ai = 0; ai < 2; ++ai) _Pragma("unroll") for (int bj = 0; bj < 2; ++bj) \
;   _Pragma("unroll") for (int m = 0; m < 4; ++m) _Pragma("unroll") for (int n = 0; n < 2; ++n) acc[ai][bj][m][n] = (f32x4){0.f, 0.f, 0.f, 0.f}; } while (0)
; __device__ __forceinline__ void phaseD(const Params& p, const int wv, const int rep) {
;     ...
;     __syncthreads();
;     {
;       const int tid = wv * 64 + lane_fresh();
;       const int r = tid >> 1, gg = tid & 1;
;       const float* ps = YPS + (size_t)(brow + r) * 32 + gg * 16;
;       f32x4 a = *(const f32x4*)ps + *(const f32x4*)(ps + 4) + *(const f32x4*)(ps + 8) + *(const f32x4*)(ps + 12);
;       rs_l[r * 2 + gg] = rsqrtf((a[0] + a[1] + a[2] + a[3]) * (1.f / 512.f) + EPS);
;     }
;     auto opnd = [&](int br, const u16*& Ap, const u16*& Bp, int& ld) {
;       if (br == 0) { Ap = GM + (size_t)brow * 512; Bp = WGM + (size_t)bcol * 512; ld = 512; }
;       else if (br == 1) { Ap = Y + (size_t)brow * 1024; Bp = WSSD + (size_t)bcol * 1024; ld = 1024; }
;       else if (br == 2) { Ap = Y + (size_t)brow * 1024 + 512; Bp = WSSD + (size_t)bcol * 1024 + 512; ld = 1024; }
;       else { Ap = XA + (size_t)brow * 512; Bp = WXA + (size_t)bcol * 512; ld = 512; }
;     };
;     Acc acc; ACC_ZERO(acc);
;     { const u16 *Ap, *Bp; int ld; opnd(0, Ap, Bp, ld); kloop_t<1, true>(Ap, ld, Bp, ld, 512, acc, wv); }
.LBB0_690:
	s_lshl_b32 s0, s89, 8
	s_and_b32 s90, s0, 0x3f00
	v_readlane_b32 s0, v250, 0
	s_barrier
	v_mbcnt_lo_u32_b32 v0, -1, 0
	v_mbcnt_hi_u32_b32 v0, -1, v0
	v_readlane_b32 s1, v250, 1
	v_add_u32_e32 v18, s0, v0
	s_add_u32 s100, s50, 0xb32e000
	s_addc_u32 s101, s51, 0
	s_lshl_b32 s98, s89, 2
	s_and_b32 s98, s98, 0x300
	s_lshl_b32 s98, s98, 1
	v_and_b32_e32 v224, 63, v18
	v_lshrrev_b32_e32 v225, 6, v18
	v_lshl_add_u32 v224, v225, 8, v224
	v_lshrrev_b32_e32 v225, 3, v224
	v_add_u32_e32 v225, s90, v225
	v_mul_lo_u32 v225, v225, s88
	v_bfe_u32 v226, v224, 2, 1
	v_lshl_add_u32 v225, v226, 11, v225
	v_and_b32_e32 v226, 3, v224
	v_lshl_add_u32 v225, v226, 7, v225
	v_add_u32_e32 v225, s98, v225
	global_load_dword v220, v225, s[100:101]
	v_add_u32_e32 v225, 0xc000, v225
	global_load_dword v221, v225, s[100:101]
	v_add_u32_e32 v225, 0xc000, v225
	global_load_dword v222, v225, s[100:101]
	v_add_u32_e32 v225, 0xc000, v225
	global_load_dword v223, v225, s[100:101]
	v_ashrrev_i32_e32 v2, 1, v18
	v_add_u32_e32 v2, s90, v2
	v_ashrrev_i32_e32 v3, 31, v2
	v_readlane_b32 s0, v251, 4
	v_lshlrev_b64 v[2:3], 7, v[2:3]
	v_readlane_b32 s1, v251, 5
	v_lshlrev_b32_e32 v0, 6, v0
	v_and_b32_e32 v0, 64, v0
	v_lshl_add_u64 v[2:3], s[0:1], 0, v[2:3]
	v_lshl_add_u64 v[14:15], v[2:3], 0, v[0:1]
	global_load_dwordx4 v[200:203], v[14:15], off
	global_load_dwordx4 v[204:207], v[14:15], off offset:16
	global_load_dwordx4 v[208:211], v[14:15], off offset:32
	s_nop 0
	global_load_dwordx4 v[212:215], v[14:15], off offset:48
	s_mov_b32 s5, 0x800000
	v_lshl_add_u32 v216, v18, 2, 16
	v_add_u32_e32 v216, 0x20000, v216
	s_lshl_b32 s0, s89, 2
	s_and_b32 s0, s0, 0x300
	s_lshl_b32 s1, s90, 10
	s_add_u32 s28, s66, s1
	s_addc_u32 s29, s67, 0
	s_lshl_b32 s4, s0, 10
	s_add_u32 s30, s70, s4
	s_addc_u32 s31, s71, 0
	s_add_u32 s6, s30, 0x20000
	s_addc_u32 s7, s31, 0
	s_mov_b32 s33, s19
	v_mbcnt_lo_u32_b32 v0, -1, 0
	v_mbcnt_hi_u32_b32 v0, -1, v0
	s_waitcnt lgkmcnt(0)
	s_waitcnt lgkmcnt(0)
	v_lshl_add_u32 v0, v0, 4, s76
	v_ashrrev_i32_e32 v2, 31, v0
	v_add_u32_e32 v3, 0x2000, v0
	v_add_u32_e32 v4, s94, v0
	v_lshrrev_b32_e32 v2, 22, v2
	v_ashrrev_i32_e32 v6, 31, v3
	v_readfirstlane_b32 s5, v4
	v_add_u32_e32 v4, 0x2000, v4
	v_add_u32_e32 v2, v0, v2
	v_lshrrev_b32_e32 v6, 22, v6
	v_readfirstlane_b32 s9, v4
	v_ashrrev_i32_e32 v2, 10, v2
	v_add_u32_e32 v4, v3, v6
	v_mul_i32_i24_e32 v6, 0x400, v2
	v_ashrrev_i32_e32 v4, 10, v4
	v_sub_u32_e32 v6, v0, v6
	v_mul_i32_i24_e32 v8, 0x400, v4
	v_lshlrev_b32_e32 v9, 3, v4
	v_lshrrev_b32_e32 v10, 4, v6
	v_sub_u32_e32 v3, v3, v8
	v_and_b32_e32 v8, 0x3ffff0, v9
	v_bitop3_b32 v6, v10, v6, 32 bitop3:0x6c
	v_lshrrev_b32_e32 v9, 4, v3
	v_ashrrev_i32_e32 v10, 31, v6
	v_bitop3_b32 v3, v9, v3, 32 bitop3:0x6c
	v_lshrrev_b32_e32 v9, 26, v10
	v_ashrrev_i32_e32 v10, 31, v3
	v_add_u32_e32 v5, 16, v0
	v_add_u32_e32 v9, v6, v9
	v_lshrrev_b32_e32 v10, 26, v10
	v_add_u32_e32 v7, 0x2000, v5
	v_lshrrev_b32_e32 v11, 6, v9
	v_and_b32_e32 v9, 0xc0, v9
	v_add_u32_e32 v10, v3, v10
	v_readfirstlane_b32 s18, v7
	v_lshlrev_b32_e32 v7, 3, v2
	v_lshlrev_b32_e32 v2, 5, v2
	v_sub_u32_e32 v6, v6, v9
	v_lshrrev_b32_e32 v9, 6, v10
	v_and_b32_e32 v10, 0xffc0, v10
	v_and_b32_e32 v2, 32, v2
	v_ashrrev_i16_sdwa v6, v187, sext(v6) dst_sel:DWORD dst_unused:UNUSED_PAD src0_sel:DWORD src1_sel:BYTE_0
	v_sub_u32_e32 v3, v3, v10
	v_add_u32_sdwa v2, v2, sext(v6) dst_sel:DWORD dst_unused:UNUSED_PAD src0_sel:DWORD src1_sel:WORD_0
	v_lshrrev_b16_e32 v6, 7, v3
	v_and_b32_e32 v6, 1, v6
	v_lshlrev_b32_e32 v4, 5, v4
	v_add_u16_e32 v3, v3, v6
	v_and_b32_e32 v7, 0x3ffff0, v7
	v_and_b32_e32 v4, 32, v4
	v_ashrrev_i16_sdwa v3, v187, sext(v3) dst_sel:DWORD dst_unused:UNUSED_PAD src0_sel:DWORD src1_sel:BYTE_0
	v_add_lshl_u32 v7, v11, v7, 10
	v_add_lshl_u32 v8, v9, v8, 10
	v_add_u32_sdwa v3, v4, sext(v3) dst_sel:DWORD dst_unused:UNUSED_PAD src0_sel:DWORD src1_sel:WORD_0
	v_lshl_add_u32 v2, v2, 1, v7
	v_lshl_add_u32 v3, v3, 1, v8
	v_mov_b32_e32 v6, v2
	v_mov_b32_e32 v4, v3
	s_mov_b32 m0, s5
	s_barrier
; __device__ __forceinline__ int lane_fresh() { int l; asm volatile("v_mbcnt_lo_u32_b32 %0, -1, 0\n\tv_mbcnt_hi_u32_b32 %0, -1, %0" : "=v"(l)); return l; }
; #define ACC_ZERO(acc) do { _Pragma("unroll") for (int ai = 0; ai < 2; ++ai) _Pragma("unroll") for (int bj = 0; bj < 2; ++bj) \
;   _Pragma("unroll") for (int m = 0; m < 4; ++m) _Pragma("unroll") for (int n = 0; n < 2; ++n) acc[ai][bj][m][n] = (f32x4){0.f, 0.f, 0.f, 0.f}; } while (0)
; __device__ __forceinline__ void phaseD(const Params& p, const int wv, const int rep) {
;     ...
;     __syncthreads();
;     {
;       const int tid = wv * 64 + lane_fresh();
;       const int r = tid >> 1, gg = tid & 1;
;       const float* ps = YPS + (size_t)(brow + r) * 32 + gg * 16;
;       f32x4 a = *(const f32x4*)ps + *(const f32x4*)(ps + 4) + *(const f32x4*)(ps + 8) + *(const f32x4*)(ps + 12);
;       rs_l[r * 2 + gg] = rsqrtf((a[0] + a[1] + a[2] + a[3]) * (1.f / 512.f) + EPS);
;     }
;     auto opnd = [&](int br, const u16*& Ap, const u16*& Bp, int& ld) {
;       if (br == 0) { Ap = GM + (size_t)brow * 512; Bp = WGM + (size_t)bcol * 512; ld = 512; }
;       else if (br == 1) { Ap = Y + (size_t)brow * 1024; Bp = WSSD + (size_t)bcol * 1024; ld = 1024; }
;       else if (br == 2) { Ap = Y + (size_t)brow * 1024 + 512; Bp = WSSD + (size_t)bcol * 1024 + 512; ld = 1024; }
;       else { Ap = XA + (size_t)brow * 512; Bp = WXA + (size_t)bcol * 512; ld = 512; }
;     };
;     Acc acc; ACC_ZERO(acc);
;     { const u16 *Ap, *Bp; int ld; opnd(0, Ap, Bp, ld); kloop_t<1, true>(Ap, ld, Bp, ld, 512, acc, wv); }
; #pragma unroll 1
;     for (int br = 0; br < 4; ++br) {
;       const u16 *Ap, *Bp; int ld; opnd(br, Ap, Bp, ld);
;       kloop_t<2>(Ap, ld, Bp, ld, 512, acc, wv);
	v_readfirstlane_b32 s8, v5
	v_mov_b32_e32 v7, v2
	global_load_lds_dwordx4 v6, s[30:31]
	s_mov_b32 m0, s9
	v_mov_b32_e32 v8, v3
	global_load_lds_dwordx4 v4, s[30:31]
	s_mov_b32 m0, s8
	v_add_u32_e32 v0, s95, v0
	v_mov_b32_e32 v9, v2
	global_load_lds_dwordx4 v7, s[28:29]
	s_mov_b32 m0, s18
	v_readfirstlane_b32 s5, v0
	v_add_u32_e32 v0, 0x2000, v0
	v_mov_b32_e32 v10, v3
	global_load_lds_dwordx4 v8, s[28:29]
	s_mov_b32 m0, s5
	v_readfirstlane_b32 s5, v0
	v_add_u32_e32 v0, 0x4000, v5
	global_load_lds_dwordx4 v9, s[6:7]
	s_mov_b32 m0, s5
	v_readfirstlane_b32 s5, v0
	global_load_lds_dwordx4 v10, s[6:7]
	s_add_u32 s6, s28, 0x20000
	v_add_u32_e32 v0, 0x6000, v5
	s_addc_u32 s7, s29, 0
	s_mov_b32 m0, s5
	v_readfirstlane_b32 s5, v0
	v_mov_b32_e32 v0, v1
	global_load_lds_dwordx4 v2, s[6:7]
	s_mov_b32 m0, s5
	s_lshl_b32 s5, s90, 11
	global_load_lds_dwordx4 v3, s[6:7]
	s_waitcnt vmcnt(10)
	v_pk_add_f32 v[200:201], v[200:201], v[204:205]
	v_pk_add_f32 v[202:203], v[202:203], v[206:207]
	s_waitcnt vmcnt(9)
	v_pk_add_f32 v[200:201], v[200:201], v[208:209]
	v_pk_add_f32 v[202:203], v[202:203], v[210:211]
	s_waitcnt vmcnt(8)
	v_pk_add_f32 v[200:201], v[200:201], v[212:213]
	v_pk_add_f32 v[202:203], v[202:203], v[214:215]
	v_add_f32_e32 v200, v200, v201
	v_add_f32_e32 v200, v202, v200
	v_add_f32_e32 v200, v203, v200
	v_fmamk_f32 v200, v200, 0x3b000000, v186
	v_mul_f32_e32 v201, 0x4b800000, v200
	v_cmp_gt_f32_e32 vcc, 0x800000, v200
	s_nop 1
	v_cndmask_b32_e32 v200, v200, v201, vcc
	v_rsq_f32_e32 v200, v200
	s_nop 0
	v_mul_f32_e32 v201, 0x45800000, v200
	v_cndmask_b32_e32 v200, v200, v201, vcc
	ds_write_b32 v216, v200
	s_add_u32 s34, s48, s5
	s_addc_u32 s35, s49, 0
	s_add_u32 s36, s34, 0x400
	s_addc_u32 s37, s35, 0
	s_lshl_b32 s5, s0, 11
	s_add_u32 s38, s72, s5
	s_addc_u32 s39, s73, 0
	s_add_u32 s40, s38, 0x400
	s_addc_u32 s41, s39, 0
	s_add_u32 s42, s68, s1
	s_addc_u32 s43, s69, 0
	s_add_u32 s44, s74, s4
	s_addc_u32 s45, s75, 0
	s_add_i32 s91, s90, s87
	s_lshl_b32 s0, s0, 1
	v_readlane_b32 s1, v250, 29
	s_add_u32 s52, s1, s0
	v_readlane_b32 s1, v250, 31
	v_mov_b32_e32 v2, v1
	v_mov_b32_e32 v3, v1
	s_addc_u32 s53, s1, 0
	v_readlane_b32 s1, v250, 33
	v_mov_b64_e32 v[20:21], v[2:3]
	v_mov_b64_e32 v[24:25], v[2:3]
	v_mov_b64_e32 v[52:53], v[2:3]
	v_mov_b64_e32 v[56:57], v[2:3]
	v_mov_b64_e32 v[68:69], v[2:3]
	v_mov_b64_e32 v[76:77], v[2:3]
	v_mov_b64_e32 v[12:13], v[2:3]
	v_mov_b64_e32 v[16:17], v[2:3]
	v_mov_b64_e32 v[28:29], v[2:3]
	v_mov_b64_e32 v[36:37], v[2:3]
	v_mov_b64_e32 v[60:61], v[2:3]
	v_mov_b64_e32 v[64:65], v[2:3]
	v_mov_b64_e32 v[88:89], v[2:3]
	v_mov_b64_e32 v[96:97], v[2:3]
	v_mov_b64_e32 v[100:101], v[2:3]
	v_mov_b64_e32 v[104:105], v[2:3]
	v_mov_b64_e32 v[128:129], v[2:3]
	v_mov_b64_e32 v[120:121], v[2:3]
	v_mov_b64_e32 v[92:93], v[2:3]
	v_mov_b64_e32 v[84:85], v[2:3]
	v_mov_b64_e32 v[48:49], v[2:3]
	v_mov_b64_e32 v[44:45], v[2:3]
	v_mov_b64_e32 v[112:113], v[2:3]
	v_mov_b64_e32 v[124:125], v[2:3]
	v_mov_b64_e32 v[116:117], v[2:3]
	v_mov_b64_e32 v[108:109], v[2:3]
	v_mov_b64_e32 v[80:81], v[2:3]
	v_mov_b64_e32 v[72:73], v[2:3]
	v_mov_b64_e32 v[40:41], v[2:3]
	v_mov_b64_e32 v[32:33], v[2:3]
	v_mov_b64_e32 v[8:9], v[2:3]
	s_add_u32 s54, s1, s0
	v_readlane_b32 s0, v250, 35
	v_mov_b64_e32 v[18:19], v[0:1]
	v_mov_b64_e32 v[22:23], v[0:1]
	v_mov_b64_e32 v[50:51], v[0:1]
	v_mov_b64_e32 v[54:55], v[0:1]
	v_mov_b64_e32 v[66:67], v[0:1]
	v_mov_b64_e32 v[74:75], v[0:1]
	v_mov_b64_e32 v[10:11], v[0:1]
	v_mov_b64_e32 v[14:15], v[0:1]
	v_mov_b64_e32 v[26:27], v[0:1]
	v_mov_b64_e32 v[34:35], v[0:1]
	v_mov_b64_e32 v[58:59], v[0:1]
	v_mov_b64_e32 v[62:63], v[0:1]
	v_mov_b64_e32 v[86:87], v[0:1]
	v_mov_b64_e32 v[94:95], v[0:1]
	v_mov_b64_e32 v[98:99], v[0:1]
	v_mov_b64_e32 v[102:103], v[0:1]
	v_mov_b64_e32 v[126:127], v[0:1]
	v_mov_b64_e32 v[118:119], v[0:1]
	v_mov_b64_e32 v[90:91], v[0:1]
	v_mov_b64_e32 v[82:83], v[0:1]
	v_mov_b64_e32 v[46:47], v[0:1]
	v_mov_b64_e32 v[42:43], v[0:1]
	v_mov_b64_e32 v[110:111], v[0:1]
	v_mov_b64_e32 v[122:123], v[0:1]
	v_mov_b64_e32 v[114:115], v[0:1]
	v_mov_b64_e32 v[106:107], v[0:1]
	v_mov_b64_e32 v[78:79], v[0:1]
	v_mov_b64_e32 v[70:71], v[0:1]
	v_mov_b64_e32 v[38:39], v[0:1]
	v_mov_b64_e32 v[30:31], v[0:1]
	v_mov_b64_e32 v[6:7], v[0:1]
	v_mov_b64_e32 v[4:5], v[2:3]
	s_addc_u32 s55, s0, 0
	v_mov_b64_e32 v[2:3], v[0:1]
	s_branch .LBB0_692
